# POST phase rewritten with all loads in flight + next-iteration prefetch; lora-up block matrix written in 16B chunks with coalesced row loads
# baseline (speedup 1.0000x reference)
.LBB0_126:
	s_and_saveexec_b64 s[30:31], s[48:49]
	s_cbranch_execz .LBB0_85
	s_load_dwordx2 s[0:1], s[28:29], 0x60
	s_load_dwordx2 s[18:19], s[28:29], 0x40
	s_load_dwordx4 s[52:55], s[28:29], 0x70
	s_load_dwordx2 s[26:27], s[28:29], 0xf0
	v_and_b32_e32 v35, 63, v160
	v_mul_u32_u24_e32 v36, 0x300, v35
	v_lshlrev_b32_e32 v35, 2, v35
	v_readfirstlane_b32 s50, v8
	s_waitcnt lgkmcnt(0)
	s_lshl_b32 s34, s22, 18
	s_add_u32 s0, s0, s34
	s_addc_u32 s1, s1, 0
	s_add_u32 s52, s52, s34
	s_addc_u32 s53, s53, 0
	s_mul_i32 s34, s22, 0xa0000
	s_add_u32 s54, s54, s34
	s_addc_u32 s55, s55, 0
	s_max_u32 s34, s22, 1
	s_add_i32 s34, s34, -1
	s_lshl_b32 s34, s34, 17
	s_add_u32 s18, s18, s34
	s_addc_u32 s19, s19, 0
	s_mul_i32 s34, s22, 0x300000
	s_add_u32 s26, s26, s34
	s_addc_u32 s27, s27, 0
	s_add_u32 s26, s26, 0x18d00000
	s_addc_u32 s27, s27, 0
.Llora_loop:
	s_cmp_lt_u32 s50, 0x30000
	s_cbranch_scc0 .Llora_done
	s_lshr_b32 s51, s50, 12
	s_and_b32 s56, s50, 0xfff
	s_lshr_b32 s57, s56, 10
	s_and_b32 s58, s56, 0x3ff
	s_mul_i32 s59, s56, 0x300
	s_lshl_b32 s60, s51, 4
	s_add_u32 s59, s59, s60
	s_add_u32 s60, s26, s59
	s_addc_u32 s61, s27, 0
	s_cmp_eq_u32 s57, 0
	s_cbranch_scc0 .Llora_t1
	s_cmp_lt_u32 s51, 8
	s_cbranch_scc0 .Llora_zero
	s_mov_b64 s[62:63], s[0:1]
	s_lshl_b32 s64, s51, 3
	s_branch .Llora_load
.Llora_t1:
	s_cmp_eq_u32 s57, 1
	s_cbranch_scc0 .Llora_t2
	s_cmp_lt_u32 s51, 8
	s_cbranch_scc1 .Llora_zero
	s_cmp_lt_u32 s51, 16
	s_cbranch_scc0 .Llora_zero
	s_mov_b64 s[62:63], s[52:53]
	s_lshl_b32 s64, s51, 3
	s_sub_u32 s64, s64, 64
	s_branch .Llora_load
.Llora_t2:
	s_cmp_eq_u32 s57, 2
	s_cbranch_scc0 .Llora_t3
	s_cmp_lt_u32 s51, 16
	s_cbranch_scc1 .Llora_zero
	s_cmp_lt_u32 s51, 36
	s_cbranch_scc0 .Llora_zero
	s_mov_b64 s[62:63], s[54:55]
	s_lshl_b32 s64, s51, 3
	s_sub_u32 s64, s64, 0x80
	s_branch .Llora_load
.Llora_t3:
	s_cmp_eq_u32 s22, 0
	s_cbranch_scc1 .Llora_zero
	s_cmp_lt_u32 s51, 36
	s_cbranch_scc1 .Llora_zero
	s_cmp_lt_u32 s51, 40
	s_cbranch_scc0 .Llora_zero
	s_mov_b64 s[62:63], s[18:19]
	s_lshl_b32 s64, s51, 3
	s_sub_u32 s64, s64, 0x120
.Llora_load:
	s_lshl_b32 s64, s64, 12
	s_lshl_b32 s65, s58, 2
	s_add_u32 s64, s64, s65
	s_add_u32 s62, s62, s64
	s_addc_u32 s63, s63, 0
	global_load_dword v0, v35, s[62:63]
	s_add_u32 s62, s62, 0x1000
	s_addc_u32 s63, s63, 0
	global_load_dword v1, v35, s[62:63]
	s_add_u32 s62, s62, 0x1000
	s_addc_u32 s63, s63, 0
	global_load_dword v2, v35, s[62:63]
	s_add_u32 s62, s62, 0x1000
	s_addc_u32 s63, s63, 0
	global_load_dword v3, v35, s[62:63]
	s_add_u32 s62, s62, 0x1000
	s_addc_u32 s63, s63, 0
	global_load_dword v4, v35, s[62:63]
	s_add_u32 s62, s62, 0x1000
	s_addc_u32 s63, s63, 0
	global_load_dword v5, v35, s[62:63]
	s_add_u32 s62, s62, 0x1000
	s_addc_u32 s63, s63, 0
	global_load_dword v6, v35, s[62:63]
	s_add_u32 s62, s62, 0x1000
	s_addc_u32 s63, s63, 0
	global_load_dword v7, v35, s[62:63]
	s_waitcnt vmcnt(0)
	v_cvt_pk_bf16_f32 v0, v0, v1
	v_cvt_pk_bf16_f32 v1, v2, v3
	v_cvt_pk_bf16_f32 v2, v4, v5
	v_cvt_pk_bf16_f32 v3, v6, v7
	s_branch .Llora_store
.Llora_zero:
	s_waitcnt vmcnt(0)
	v_mov_b32_e32 v0, 0
	v_mov_b32_e32 v1, 0
	v_mov_b32_e32 v2, 0
	v_mov_b32_e32 v3, 0
.Llora_store:
	s_nop 0
	global_store_dwordx4 v36, v[0:3], s[60:61]
	s_add_u32 s50, s50, s82
	s_branch .Llora_loop
.Llora_done:
	s_waitcnt vmcnt(0)
	s_branch .LBB0_85

.LBB0_172:
	s_and_b64 vcc, exec, s[6:7]
	s_cbranch_vccz .LBB0_182
	s_cmp_eq_u32 s86, 4
	s_mov_b64 s[4:5], -1
	s_cbranch_scc0 .LBB0_182
	v_ashrrev_i32_e32 v0, 6, v160
	v_lshl_add_u32 v97, s12, 3, v0
	s_mov_b32 s0, 0x8000
	v_cmp_gt_i32_e32 vcc, s0, v97
	s_and_saveexec_b64 s[4:5], vcc
	s_cbranch_execz .LBB0_181
	s_load_dwordx2 s[6:7], s[28:29], 0xf0
	s_load_dwordx2 s[0:1], s[28:29], 0x20
	s_load_dwordx8 s[40:47], s[28:29], 0x88
	v_readlane_b32 s9, v254, 22
	v_readfirstlane_b32 s13, v97
	v_and_b32_e32 v1, 63, v160
	v_lshrrev_b32_e32 v2, 3, v1
	s_and_b32 s18, s13, 1
	s_lshl_b32 s18, s18, 3
	v_add_u32_e32 v2, s18, v2
	v_and_b32_e32 v1, 7, v1
	v_lshlrev_b32_e32 v1, 3, v1
	v_lshl_or_b32 v1, v2, 6, v1
	v_lshlrev_b32_e32 v0, 1, v1
	v_lshlrev_b32_e32 v1, 2, v1
	s_waitcnt lgkmcnt(0)
	s_mul_i32 s18, s9, 0x3480
	s_add_u32 s0, s0, s18
	s_addc_u32 s1, s1, 0
	s_lshl_b32 s18, s9, 12
	s_add_u32 s40, s40, s18
	s_addc_u32 s41, s41, 0
	s_add_u32 s42, s42, s18
	s_addc_u32 s43, s43, 0
	s_add_u32 s44, s44, s18
	s_addc_u32 s45, s45, 0
	s_add_u32 s46, s46, s18
	s_addc_u32 s47, s47, 0
	global_load_dwordx4 v[8:11], v1, s[0:1]
	global_load_dwordx4 v[12:15], v1, s[0:1] offset:16
	s_add_u32 s0, s0, 0x1000
	s_addc_u32 s1, s1, 0
	global_load_dwordx4 v[16:19], v1, s[0:1]
	global_load_dwordx4 v[20:23], v1, s[0:1] offset:16
	s_add_u32 s0, s0, 0x1000
	s_addc_u32 s1, s1, 0
	global_load_dwordx4 v[24:27], v1, s[0:1]
	global_load_dwordx4 v[28:31], v1, s[0:1] offset:16
	global_load_dwordx4 v[32:35], v1, s[40:41]
	global_load_dwordx4 v[36:39], v1, s[40:41] offset:16
	global_load_dwordx4 v[40:43], v1, s[42:43]
	global_load_dwordx4 v[44:47], v1, s[42:43] offset:16
	global_load_dwordx4 v[48:51], v1, s[44:45]
	global_load_dwordx4 v[52:55], v1, s[44:45] offset:16
	global_load_dwordx4 v[56:59], v1, s[46:47]
	global_load_dwordx4 v[60:63], v1, s[46:47] offset:16
	v_mov_b32_e32 v67, 0x3a27c5ac
	v_mov_b32_e32 v68, 0xbc800000
	v_mov_b32_e32 v69, 0xbc800000
	s_add_u32 s14, s6, 0x28701000
	s_addc_u32 s15, s7, 0
	s_cmp_lg_u32 s9, 0
	s_mov_b32 s9, s13
	s_cbranch_scc0 .Lpost_nov
	s_lshr_b32 s0, s9, 1
	s_mul_i32 s1, s0, 0x2400
	s_add_u32 s18, s14, s1
	s_addc_u32 s19, s15, 0
	s_and_b32 s1, s0, 0xfff
	s_cmp_eq_u32 s1, 0
	s_cselect_b32 s1, 0, 0x2400
	s_sub_u32 s20, s18, s1
	s_subb_u32 s21, s19, 0
	s_lshl_b32 s1, s0, 11
	s_add_u32 s22, s6, s1
	s_addc_u32 s23, s7, 0
	s_add_u32 s38, s22, 0x23b00000
	s_addc_u32 s39, s23, 0
	s_add_u32 s34, s22, 0x26700000
	s_addc_u32 s35, s23, 0
	s_add_u32 s24, s22, 0x35700000
	s_addc_u32 s25, s23, 0
	s_add_u32 s30, s22, 0x37700000
	s_addc_u32 s31, s23, 0
	s_add_u32 s22, s22, 0x33700000
	s_addc_u32 s23, s23, 0
	global_load_dwordx4 v[72:75], v0, s[18:19] offset:-2048
	global_load_dwordx4 v[76:79], v0, s[18:19]
	global_load_dwordx4 v[80:83], v0, s[18:19] offset:2048
	global_load_dwordx4 v[84:87], v0, s[20:21] offset:-2048
	global_load_dwordx4 v[88:91], v0, s[20:21]
	global_load_dwordx4 v[92:95], v0, s[20:21] offset:2048
	global_load_dwordx4 v[96:99], v0, s[22:23]
	global_load_dwordx4 v[100:103], v0, s[24:25]
	global_load_dwordx4 v[104:107], v0, s[38:39]
	global_load_dwordx4 v[108:111], v0, s[34:35]
	global_load_dwordx4 v[112:115], v0, s[30:31]
.Lpost_loop_hv:
	s_add_i32 s13, s9, s8
	s_cmp_lt_i32 s13, 0x8000
	s_cbranch_scc0 .Lpost_last_hv_0
	s_lshr_b32 s0, s13, 1
	s_mul_i32 s1, s0, 0x2400
	s_add_u32 s18, s14, s1
	s_addc_u32 s19, s15, 0
	s_and_b32 s1, s0, 0xfff
	s_cmp_eq_u32 s1, 0
	s_cselect_b32 s1, 0, 0x2400
	s_sub_u32 s20, s18, s1
	s_subb_u32 s21, s19, 0
	s_lshl_b32 s1, s0, 11
	s_add_u32 s22, s6, s1
	s_addc_u32 s23, s7, 0
	s_add_u32 s38, s22, 0x23b00000
	s_addc_u32 s39, s23, 0
	s_add_u32 s34, s22, 0x26700000
	s_addc_u32 s35, s23, 0
	s_add_u32 s24, s22, 0x35700000
	s_addc_u32 s25, s23, 0
	s_add_u32 s30, s22, 0x37700000
	s_addc_u32 s31, s23, 0
	s_add_u32 s22, s22, 0x33700000
	s_addc_u32 s23, s23, 0
	global_load_dwordx4 v[116:119], v0, s[18:19] offset:-2048
	global_load_dwordx4 v[120:123], v0, s[18:19]
	global_load_dwordx4 v[124:127], v0, s[18:19] offset:2048
	global_load_dwordx4 v[128:131], v0, s[20:21] offset:-2048
	global_load_dwordx4 v[132:135], v0, s[20:21]
	global_load_dwordx4 v[136:139], v0, s[20:21] offset:2048
	global_load_dwordx4 v[140:143], v0, s[22:23]
	global_load_dwordx4 v[144:147], v0, s[24:25]
	global_load_dwordx4 v[148:151], v0, s[38:39]
	global_load_dwordx4 v[152:155], v0, s[34:35]
	global_load_dwordx4 v[164:167], v0, s[30:31]
	s_waitcnt vmcnt(11)
	s_branch .Lpost_go_hv_0

.Lpost_go_hv_0:
	s_lshr_b32 s0, s9, 1
	s_and_b32 s0, s0, 0xfff
	s_cmp_eq_u32 s0, 0
	s_cselect_b32 s44, 1, 0
	v_lshlrev_b32_e32 v168, 16, v72
	v_and_b32_e32 v169, 0xffff0000, v72
	v_lshlrev_b32_e32 v170, 16, v73
	v_and_b32_e32 v171, 0xffff0000, v73
	v_lshlrev_b32_e32 v172, 16, v74
	v_and_b32_e32 v173, 0xffff0000, v74
	v_lshlrev_b32_e32 v174, 16, v75
	v_and_b32_e32 v175, 0xffff0000, v75
	s_cmp_eq_u32 s44, 1
	s_cbranch_scc1 .Lpz_hv0_168
	v_lshlrev_b32_e32 v232, 16, v84
	v_and_b32_e32 v233, 0xffff0000, v84
	v_lshlrev_b32_e32 v234, 16, v85
	v_and_b32_e32 v235, 0xffff0000, v85
	v_lshlrev_b32_e32 v236, 16, v86
	v_and_b32_e32 v237, 0xffff0000, v86
	v_lshlrev_b32_e32 v238, 16, v87
	v_and_b32_e32 v239, 0xffff0000, v87
	s_branch .Lpd_hv0_168
.Lpz_hv0_168:
	v_mov_b32_e32 v232, 0
	v_mov_b32_e32 v233, 0
	v_mov_b32_e32 v234, 0
	v_mov_b32_e32 v235, 0
	v_mov_b32_e32 v236, 0
	v_mov_b32_e32 v237, 0
	v_mov_b32_e32 v238, 0
	v_mov_b32_e32 v239, 0
.Lpd_hv0_168:
	v_pk_add_f32 v[232:233], v[232:233], v[168:169] neg_lo:[0,1] neg_hi:[0,1]
	v_pk_add_f32 v[234:235], v[234:235], v[170:171] neg_lo:[0,1] neg_hi:[0,1]
	v_pk_add_f32 v[236:237], v[236:237], v[172:173] neg_lo:[0,1] neg_hi:[0,1]
	v_pk_add_f32 v[238:239], v[238:239], v[174:175] neg_lo:[0,1] neg_hi:[0,1]
	v_pk_fma_f32 v[168:169], v[232:233], v[8:9], v[168:169]
	v_pk_fma_f32 v[170:171], v[234:235], v[10:11], v[170:171]
	v_pk_fma_f32 v[172:173], v[236:237], v[12:13], v[172:173]
	v_pk_fma_f32 v[174:175], v[238:239], v[14:15], v[174:175]
	v_lshlrev_b32_e32 v176, 16, v76
	v_and_b32_e32 v177, 0xffff0000, v76
	v_lshlrev_b32_e32 v178, 16, v77
	v_and_b32_e32 v179, 0xffff0000, v77
	v_lshlrev_b32_e32 v180, 16, v78
	v_and_b32_e32 v181, 0xffff0000, v78
	v_lshlrev_b32_e32 v182, 16, v79
	v_and_b32_e32 v183, 0xffff0000, v79
	s_cmp_eq_u32 s44, 1
	s_cbranch_scc1 .Lpz_hv0_176
	v_lshlrev_b32_e32 v232, 16, v88
	v_and_b32_e32 v233, 0xffff0000, v88
	v_lshlrev_b32_e32 v234, 16, v89
	v_and_b32_e32 v235, 0xffff0000, v89
	v_lshlrev_b32_e32 v236, 16, v90
	v_and_b32_e32 v237, 0xffff0000, v90
	v_lshlrev_b32_e32 v238, 16, v91
	v_and_b32_e32 v239, 0xffff0000, v91
	s_branch .Lpd_hv0_176

.Lpd_hv0_176:
	v_pk_add_f32 v[232:233], v[232:233], v[176:177] neg_lo:[0,1] neg_hi:[0,1]
	v_pk_add_f32 v[234:235], v[234:235], v[178:179] neg_lo:[0,1] neg_hi:[0,1]
	v_pk_add_f32 v[236:237], v[236:237], v[180:181] neg_lo:[0,1] neg_hi:[0,1]
	v_pk_add_f32 v[238:239], v[238:239], v[182:183] neg_lo:[0,1] neg_hi:[0,1]
	v_pk_fma_f32 v[176:177], v[232:233], v[16:17], v[176:177]
	v_pk_fma_f32 v[178:179], v[234:235], v[18:19], v[178:179]
	v_pk_fma_f32 v[180:181], v[236:237], v[20:21], v[180:181]
	v_pk_fma_f32 v[182:183], v[238:239], v[22:23], v[182:183]
	v_lshlrev_b32_e32 v184, 16, v80
	v_and_b32_e32 v185, 0xffff0000, v80
	v_lshlrev_b32_e32 v186, 16, v81
	v_and_b32_e32 v187, 0xffff0000, v81
	v_lshlrev_b32_e32 v188, 16, v82
	v_and_b32_e32 v189, 0xffff0000, v82
	v_lshlrev_b32_e32 v190, 16, v83
	v_and_b32_e32 v191, 0xffff0000, v83
	s_cmp_eq_u32 s44, 1
	s_cbranch_scc1 .Lpz_hv0_184
	v_lshlrev_b32_e32 v232, 16, v92
	v_and_b32_e32 v233, 0xffff0000, v92
	v_lshlrev_b32_e32 v234, 16, v93
	v_and_b32_e32 v235, 0xffff0000, v93
	v_lshlrev_b32_e32 v236, 16, v94
	v_and_b32_e32 v237, 0xffff0000, v94
	v_lshlrev_b32_e32 v238, 16, v95
	v_and_b32_e32 v239, 0xffff0000, v95
	s_branch .Lpd_hv0_184

.Lpd_hv0_184:
	v_pk_add_f32 v[232:233], v[232:233], v[184:185] neg_lo:[0,1] neg_hi:[0,1]
	v_pk_add_f32 v[234:235], v[234:235], v[186:187] neg_lo:[0,1] neg_hi:[0,1]
	v_pk_add_f32 v[236:237], v[236:237], v[188:189] neg_lo:[0,1] neg_hi:[0,1]
	v_pk_add_f32 v[238:239], v[238:239], v[190:191] neg_lo:[0,1] neg_hi:[0,1]
	v_pk_fma_f32 v[184:185], v[232:233], v[24:25], v[184:185]
	v_pk_fma_f32 v[186:187], v[234:235], v[26:27], v[186:187]
	v_pk_fma_f32 v[188:189], v[236:237], v[28:29], v[188:189]
	v_pk_fma_f32 v[190:191], v[238:239], v[30:31], v[190:191]
	v_lshlrev_b32_e32 v208, 16, v96
	v_and_b32_e32 v209, 0xffff0000, v96
	v_lshlrev_b32_e32 v210, 16, v97
	v_and_b32_e32 v211, 0xffff0000, v97
	v_lshlrev_b32_e32 v212, 16, v98
	v_and_b32_e32 v213, 0xffff0000, v98
	v_lshlrev_b32_e32 v214, 16, v99
	v_and_b32_e32 v215, 0xffff0000, v99
	v_lshlrev_b32_e32 v216, 16, v100
	v_and_b32_e32 v217, 0xffff0000, v100
	v_lshlrev_b32_e32 v218, 16, v101
	v_and_b32_e32 v219, 0xffff0000, v101
	v_lshlrev_b32_e32 v220, 16, v102
	v_and_b32_e32 v221, 0xffff0000, v102
	v_lshlrev_b32_e32 v222, 16, v103
	v_and_b32_e32 v223, 0xffff0000, v103
	v_lshlrev_b32_e32 v232, 16, v108
	v_and_b32_e32 v233, 0xffff0000, v108
	v_lshlrev_b32_e32 v234, 16, v109
	v_and_b32_e32 v235, 0xffff0000, v109
	v_lshlrev_b32_e32 v236, 16, v110
	v_and_b32_e32 v237, 0xffff0000, v110
	v_lshlrev_b32_e32 v238, 16, v111
	v_and_b32_e32 v239, 0xffff0000, v111
	v_lshlrev_b32_e32 v240, 16, v112
	v_and_b32_e32 v241, 0xffff0000, v112
	v_lshlrev_b32_e32 v242, 16, v113
	v_and_b32_e32 v243, 0xffff0000, v113
	v_lshlrev_b32_e32 v244, 16, v114
	v_and_b32_e32 v245, 0xffff0000, v114
	v_lshlrev_b32_e32 v246, 16, v115
	v_and_b32_e32 v247, 0xffff0000, v115
	v_pk_add_f32 v[232:233], v[232:233], v[184:185] neg_lo:[0,1] neg_hi:[0,1]
	v_pk_add_f32 v[234:235], v[234:235], v[186:187] neg_lo:[0,1] neg_hi:[0,1]
	v_pk_add_f32 v[236:237], v[236:237], v[188:189] neg_lo:[0,1] neg_hi:[0,1]
	v_pk_add_f32 v[238:239], v[238:239], v[190:191] neg_lo:[0,1] neg_hi:[0,1]
	v_pk_fma_f32 v[184:185], v[232:233], v[240:241], v[184:185]
	v_pk_fma_f32 v[186:187], v[234:235], v[242:243], v[186:187]
	v_pk_fma_f32 v[188:189], v[236:237], v[244:245], v[188:189]
	v_pk_fma_f32 v[190:191], v[238:239], v[246:247], v[190:191]
	v_pk_add_f32 v[240:241], v[208:209], -1.0 op_sel_hi:[1,0]
	v_pk_add_f32 v[242:243], v[210:211], -1.0 op_sel_hi:[1,0]
	v_pk_add_f32 v[244:245], v[212:213], -1.0 op_sel_hi:[1,0]
	v_pk_add_f32 v[246:247], v[214:215], -1.0 op_sel_hi:[1,0]
	v_pk_fma_f32 v[240:241], v[240:241], v[32:33], 1.0 op_sel_hi:[1,1,0]
	v_pk_fma_f32 v[242:243], v[242:243], v[34:35], 1.0 op_sel_hi:[1,1,0]
	v_pk_fma_f32 v[244:245], v[244:245], v[36:37], 1.0 op_sel_hi:[1,1,0]
	v_pk_fma_f32 v[246:247], v[246:247], v[38:39], 1.0 op_sel_hi:[1,1,0]
	v_pk_mul_f32 v[176:177], v[176:177], v[240:241]
	v_pk_mul_f32 v[178:179], v[178:179], v[242:243]
	v_pk_mul_f32 v[180:181], v[180:181], v[244:245]
	v_pk_mul_f32 v[182:183], v[182:183], v[246:247]
	v_pk_mul_f32 v[240:241], v[168:169], v[176:177]
	v_pk_mul_f32 v[242:243], v[170:171], v[178:179]
	v_pk_mul_f32 v[244:245], v[172:173], v[180:181]
	v_pk_mul_f32 v[246:247], v[174:175], v[182:183]
	v_pk_mul_f32 v[240:241], v[240:241], v[40:41]
	v_pk_mul_f32 v[242:243], v[242:243], v[42:43]
	v_pk_mul_f32 v[244:245], v[244:245], v[44:45]
	v_pk_mul_f32 v[246:247], v[246:247], v[46:47]
	v_pk_add_f32 v[168:169], v[240:241], v[242:243]
	v_pk_add_f32 v[170:171], v[244:245], v[246:247]
	v_pk_add_f32 v[168:169], v[168:169], v[170:171]
	v_add_f32_e32 v248, v168, v169
	s_nop 1
	v_add_f32_dpp v248, v248, v248 quad_perm:[1,0,3,2] row_mask:0xf bank_mask:0xf bound_ctrl:1
	s_nop 1
	v_add_f32_dpp v248, v248, v248 quad_perm:[2,3,0,1] row_mask:0xf bank_mask:0xf bound_ctrl:1
	s_nop 1
	v_add_f32_dpp v248, v248, v248 row_half_mirror row_mask:0xf bank_mask:0xf bound_ctrl:1
	v_lshlrev_b32_e32 v232, 16, v104
	v_and_b32_e32 v233, 0xffff0000, v104
	v_lshlrev_b32_e32 v234, 16, v105
	v_and_b32_e32 v235, 0xffff0000, v105
	v_lshlrev_b32_e32 v236, 16, v106
	v_and_b32_e32 v237, 0xffff0000, v106
	v_lshlrev_b32_e32 v238, 16, v107
	v_and_b32_e32 v239, 0xffff0000, v107
	v_pk_add_f32 v[168:169], v[232:233], v[234:235]
	v_pk_add_f32 v[170:171], v[236:237], v[238:239]
	v_pk_add_f32 v[168:169], v[168:169], v[170:171]
	v_add_f32_e32 v250, v168, v169
	s_nop 1
	v_add_f32_dpp v250, v250, v250 quad_perm:[1,0,3,2] row_mask:0xf bank_mask:0xf bound_ctrl:1
	s_nop 1
	v_add_f32_dpp v250, v250, v250 quad_perm:[2,3,0,1] row_mask:0xf bank_mask:0xf bound_ctrl:1
	s_nop 1
	v_add_f32_dpp v250, v250, v250 row_half_mirror row_mask:0xf bank_mask:0xf bound_ctrl:1
	v_pk_fma_f32 v[232:233], v[250:251], v[68:69], v[232:233] op_sel_hi:[0,1,1]
	v_pk_fma_f32 v[234:235], v[250:251], v[68:69], v[234:235] op_sel_hi:[0,1,1]
	v_pk_fma_f32 v[236:237], v[250:251], v[68:69], v[236:237] op_sel_hi:[0,1,1]
	v_pk_fma_f32 v[238:239], v[250:251], v[68:69], v[238:239] op_sel_hi:[0,1,1]
	v_pk_mul_f32 v[240:241], v[232:233], v[232:233]
	v_pk_mul_f32 v[242:243], v[234:235], v[234:235]
	v_pk_mul_f32 v[244:245], v[236:237], v[236:237]
	v_pk_mul_f32 v[246:247], v[238:239], v[238:239]
	v_pk_add_f32 v[168:169], v[240:241], v[242:243]
	v_pk_add_f32 v[170:171], v[244:245], v[246:247]
	v_pk_add_f32 v[168:169], v[168:169], v[170:171]
	v_add_f32_e32 v66, v168, v169
	s_nop 1
	v_add_f32_dpp v66, v66, v66 quad_perm:[1,0,3,2] row_mask:0xf bank_mask:0xf bound_ctrl:1
	s_nop 1
	v_add_f32_dpp v66, v66, v66 quad_perm:[2,3,0,1] row_mask:0xf bank_mask:0xf bound_ctrl:1
	s_nop 1
	v_add_f32_dpp v66, v66, v66 row_half_mirror row_mask:0xf bank_mask:0xf bound_ctrl:1
	s_nop 0
	v_fmamk_f32 v66, v66, 0x3c800000, v67
	v_rsq_f32_e32 v66, v66
	s_nop 0
	v_pk_mul_f32 v[232:233], v[232:233], v[66:67] op_sel_hi:[1,0]
	v_pk_mul_f32 v[234:235], v[234:235], v[66:67] op_sel_hi:[1,0]
	v_pk_mul_f32 v[236:237], v[236:237], v[66:67] op_sel_hi:[1,0]
	v_pk_mul_f32 v[238:239], v[238:239], v[66:67] op_sel_hi:[1,0]
	v_pk_fma_f32 v[232:233], v[232:233], v[48:49], v[56:57]
	v_pk_fma_f32 v[234:235], v[234:235], v[50:51], v[58:59]
	v_pk_fma_f32 v[236:237], v[236:237], v[52:53], v[60:61]
	v_pk_fma_f32 v[238:239], v[238:239], v[54:55], v[62:63]
	v_pk_fma_f32 v[232:233], v[184:185], v[248:249], v[232:233] op_sel_hi:[1,0,1]
	v_pk_fma_f32 v[234:235], v[186:187], v[248:249], v[234:235] op_sel_hi:[1,0,1]
	v_pk_fma_f32 v[236:237], v[188:189], v[248:249], v[236:237] op_sel_hi:[1,0,1]
	v_pk_fma_f32 v[238:239], v[190:191], v[248:249], v[238:239] op_sel_hi:[1,0,1]
	v_pk_mul_f32 v[232:233], v[232:233], v[216:217]
	v_pk_mul_f32 v[234:235], v[234:235], v[218:219]
	v_pk_mul_f32 v[236:237], v[236:237], v[220:221]
	v_pk_mul_f32 v[238:239], v[238:239], v[222:223]
	v_cvt_pk_bf16_f32 v192, v232, v233
	v_cvt_pk_bf16_f32 v193, v234, v235
	v_cvt_pk_bf16_f32 v194, v236, v237
	v_cvt_pk_bf16_f32 v195, v238, v239
	s_lshr_b32 s0, s9, 1
	s_lshl_b32 s0, s0, 12
	s_add_u32 s42, s6, s0
	s_addc_u32 s43, s7, 0
	s_add_u32 s42, s42, 0x1fb00800
	s_addc_u32 s43, s43, 0
	global_store_dwordx4 v0, v[192:195], s[42:43]
	s_mov_b32 s9, s13
	s_cmp_lt_i32 s9, 0x8000
	s_cbranch_scc0 .Lpost_done
	s_add_i32 s13, s9, s8
	s_cmp_lt_i32 s13, 0x8000
	s_cbranch_scc0 .Lpost_last_hv_1
	s_lshr_b32 s0, s13, 1
	s_mul_i32 s1, s0, 0x2400
	s_add_u32 s18, s14, s1
	s_addc_u32 s19, s15, 0
	s_and_b32 s1, s0, 0xfff
	s_cmp_eq_u32 s1, 0
	s_cselect_b32 s1, 0, 0x2400
	s_sub_u32 s20, s18, s1
	s_subb_u32 s21, s19, 0
	s_lshl_b32 s1, s0, 11
	s_add_u32 s22, s6, s1
	s_addc_u32 s23, s7, 0
	s_add_u32 s38, s22, 0x23b00000
	s_addc_u32 s39, s23, 0
	s_add_u32 s34, s22, 0x26700000
	s_addc_u32 s35, s23, 0
	s_add_u32 s24, s22, 0x35700000
	s_addc_u32 s25, s23, 0
	s_add_u32 s30, s22, 0x37700000
	s_addc_u32 s31, s23, 0
	s_add_u32 s22, s22, 0x33700000
	s_addc_u32 s23, s23, 0
	global_load_dwordx4 v[72:75], v0, s[18:19] offset:-2048
	global_load_dwordx4 v[76:79], v0, s[18:19]
	global_load_dwordx4 v[80:83], v0, s[18:19] offset:2048
	global_load_dwordx4 v[84:87], v0, s[20:21] offset:-2048
	global_load_dwordx4 v[88:91], v0, s[20:21]
	global_load_dwordx4 v[92:95], v0, s[20:21] offset:2048
	global_load_dwordx4 v[96:99], v0, s[22:23]
	global_load_dwordx4 v[100:103], v0, s[24:25]
	global_load_dwordx4 v[104:107], v0, s[38:39]
	global_load_dwordx4 v[108:111], v0, s[34:35]
	global_load_dwordx4 v[112:115], v0, s[30:31]
	s_waitcnt vmcnt(11)
	s_branch .Lpost_go_hv_1

.Lpost_go_hv_1:
	s_lshr_b32 s0, s9, 1
	s_and_b32 s0, s0, 0xfff
	s_cmp_eq_u32 s0, 0
	s_cselect_b32 s44, 1, 0
	v_lshlrev_b32_e32 v168, 16, v116
	v_and_b32_e32 v169, 0xffff0000, v116
	v_lshlrev_b32_e32 v170, 16, v117
	v_and_b32_e32 v171, 0xffff0000, v117
	v_lshlrev_b32_e32 v172, 16, v118
	v_and_b32_e32 v173, 0xffff0000, v118
	v_lshlrev_b32_e32 v174, 16, v119
	v_and_b32_e32 v175, 0xffff0000, v119
	s_cmp_eq_u32 s44, 1
	s_cbranch_scc1 .Lpz_hv1_168
	v_lshlrev_b32_e32 v232, 16, v128
	v_and_b32_e32 v233, 0xffff0000, v128
	v_lshlrev_b32_e32 v234, 16, v129
	v_and_b32_e32 v235, 0xffff0000, v129
	v_lshlrev_b32_e32 v236, 16, v130
	v_and_b32_e32 v237, 0xffff0000, v130
	v_lshlrev_b32_e32 v238, 16, v131
	v_and_b32_e32 v239, 0xffff0000, v131
	s_branch .Lpd_hv1_168

.Lpd_hv1_168:
	v_pk_add_f32 v[232:233], v[232:233], v[168:169] neg_lo:[0,1] neg_hi:[0,1]
	v_pk_add_f32 v[234:235], v[234:235], v[170:171] neg_lo:[0,1] neg_hi:[0,1]
	v_pk_add_f32 v[236:237], v[236:237], v[172:173] neg_lo:[0,1] neg_hi:[0,1]
	v_pk_add_f32 v[238:239], v[238:239], v[174:175] neg_lo:[0,1] neg_hi:[0,1]
	v_pk_fma_f32 v[168:169], v[232:233], v[8:9], v[168:169]
	v_pk_fma_f32 v[170:171], v[234:235], v[10:11], v[170:171]
	v_pk_fma_f32 v[172:173], v[236:237], v[12:13], v[172:173]
	v_pk_fma_f32 v[174:175], v[238:239], v[14:15], v[174:175]
	v_lshlrev_b32_e32 v176, 16, v120
	v_and_b32_e32 v177, 0xffff0000, v120
	v_lshlrev_b32_e32 v178, 16, v121
	v_and_b32_e32 v179, 0xffff0000, v121
	v_lshlrev_b32_e32 v180, 16, v122
	v_and_b32_e32 v181, 0xffff0000, v122
	v_lshlrev_b32_e32 v182, 16, v123
	v_and_b32_e32 v183, 0xffff0000, v123
	s_cmp_eq_u32 s44, 1
	s_cbranch_scc1 .Lpz_hv1_176
	v_lshlrev_b32_e32 v232, 16, v132
	v_and_b32_e32 v233, 0xffff0000, v132
	v_lshlrev_b32_e32 v234, 16, v133
	v_and_b32_e32 v235, 0xffff0000, v133
	v_lshlrev_b32_e32 v236, 16, v134
	v_and_b32_e32 v237, 0xffff0000, v134
	v_lshlrev_b32_e32 v238, 16, v135
	v_and_b32_e32 v239, 0xffff0000, v135
	s_branch .Lpd_hv1_176

.Lpd_hv1_176:
	v_pk_add_f32 v[232:233], v[232:233], v[176:177] neg_lo:[0,1] neg_hi:[0,1]
	v_pk_add_f32 v[234:235], v[234:235], v[178:179] neg_lo:[0,1] neg_hi:[0,1]
	v_pk_add_f32 v[236:237], v[236:237], v[180:181] neg_lo:[0,1] neg_hi:[0,1]
	v_pk_add_f32 v[238:239], v[238:239], v[182:183] neg_lo:[0,1] neg_hi:[0,1]
	v_pk_fma_f32 v[176:177], v[232:233], v[16:17], v[176:177]
	v_pk_fma_f32 v[178:179], v[234:235], v[18:19], v[178:179]
	v_pk_fma_f32 v[180:181], v[236:237], v[20:21], v[180:181]
	v_pk_fma_f32 v[182:183], v[238:239], v[22:23], v[182:183]
	v_lshlrev_b32_e32 v184, 16, v124
	v_and_b32_e32 v185, 0xffff0000, v124
	v_lshlrev_b32_e32 v186, 16, v125
	v_and_b32_e32 v187, 0xffff0000, v125
	v_lshlrev_b32_e32 v188, 16, v126
	v_and_b32_e32 v189, 0xffff0000, v126
	v_lshlrev_b32_e32 v190, 16, v127
	v_and_b32_e32 v191, 0xffff0000, v127
	s_cmp_eq_u32 s44, 1
	s_cbranch_scc1 .Lpz_hv1_184
	v_lshlrev_b32_e32 v232, 16, v136
	v_and_b32_e32 v233, 0xffff0000, v136
	v_lshlrev_b32_e32 v234, 16, v137
	v_and_b32_e32 v235, 0xffff0000, v137
	v_lshlrev_b32_e32 v236, 16, v138
	v_and_b32_e32 v237, 0xffff0000, v138
	v_lshlrev_b32_e32 v238, 16, v139
	v_and_b32_e32 v239, 0xffff0000, v139
	s_branch .Lpd_hv1_184

.Lpd_hv1_184:
	v_pk_add_f32 v[232:233], v[232:233], v[184:185] neg_lo:[0,1] neg_hi:[0,1]
	v_pk_add_f32 v[234:235], v[234:235], v[186:187] neg_lo:[0,1] neg_hi:[0,1]
	v_pk_add_f32 v[236:237], v[236:237], v[188:189] neg_lo:[0,1] neg_hi:[0,1]
	v_pk_add_f32 v[238:239], v[238:239], v[190:191] neg_lo:[0,1] neg_hi:[0,1]
	v_pk_fma_f32 v[184:185], v[232:233], v[24:25], v[184:185]
	v_pk_fma_f32 v[186:187], v[234:235], v[26:27], v[186:187]
	v_pk_fma_f32 v[188:189], v[236:237], v[28:29], v[188:189]
	v_pk_fma_f32 v[190:191], v[238:239], v[30:31], v[190:191]
	v_lshlrev_b32_e32 v208, 16, v140
	v_and_b32_e32 v209, 0xffff0000, v140
	v_lshlrev_b32_e32 v210, 16, v141
	v_and_b32_e32 v211, 0xffff0000, v141
	v_lshlrev_b32_e32 v212, 16, v142
	v_and_b32_e32 v213, 0xffff0000, v142
	v_lshlrev_b32_e32 v214, 16, v143
	v_and_b32_e32 v215, 0xffff0000, v143
	v_lshlrev_b32_e32 v216, 16, v144
	v_and_b32_e32 v217, 0xffff0000, v144
	v_lshlrev_b32_e32 v218, 16, v145
	v_and_b32_e32 v219, 0xffff0000, v145
	v_lshlrev_b32_e32 v220, 16, v146
	v_and_b32_e32 v221, 0xffff0000, v146
	v_lshlrev_b32_e32 v222, 16, v147
	v_and_b32_e32 v223, 0xffff0000, v147
	v_lshlrev_b32_e32 v232, 16, v152
	v_and_b32_e32 v233, 0xffff0000, v152
	v_lshlrev_b32_e32 v234, 16, v153
	v_and_b32_e32 v235, 0xffff0000, v153
	v_lshlrev_b32_e32 v236, 16, v154
	v_and_b32_e32 v237, 0xffff0000, v154
	v_lshlrev_b32_e32 v238, 16, v155
	v_and_b32_e32 v239, 0xffff0000, v155
	v_lshlrev_b32_e32 v240, 16, v164
	v_and_b32_e32 v241, 0xffff0000, v164
	v_lshlrev_b32_e32 v242, 16, v165
	v_and_b32_e32 v243, 0xffff0000, v165
	v_lshlrev_b32_e32 v244, 16, v166
	v_and_b32_e32 v245, 0xffff0000, v166
	v_lshlrev_b32_e32 v246, 16, v167
	v_and_b32_e32 v247, 0xffff0000, v167
	v_pk_add_f32 v[232:233], v[232:233], v[184:185] neg_lo:[0,1] neg_hi:[0,1]
	v_pk_add_f32 v[234:235], v[234:235], v[186:187] neg_lo:[0,1] neg_hi:[0,1]
	v_pk_add_f32 v[236:237], v[236:237], v[188:189] neg_lo:[0,1] neg_hi:[0,1]
	v_pk_add_f32 v[238:239], v[238:239], v[190:191] neg_lo:[0,1] neg_hi:[0,1]
	v_pk_fma_f32 v[184:185], v[232:233], v[240:241], v[184:185]
	v_pk_fma_f32 v[186:187], v[234:235], v[242:243], v[186:187]
	v_pk_fma_f32 v[188:189], v[236:237], v[244:245], v[188:189]
	v_pk_fma_f32 v[190:191], v[238:239], v[246:247], v[190:191]
	v_pk_add_f32 v[240:241], v[208:209], -1.0 op_sel_hi:[1,0]
	v_pk_add_f32 v[242:243], v[210:211], -1.0 op_sel_hi:[1,0]
	v_pk_add_f32 v[244:245], v[212:213], -1.0 op_sel_hi:[1,0]
	v_pk_add_f32 v[246:247], v[214:215], -1.0 op_sel_hi:[1,0]
	v_pk_fma_f32 v[240:241], v[240:241], v[32:33], 1.0 op_sel_hi:[1,1,0]
	v_pk_fma_f32 v[242:243], v[242:243], v[34:35], 1.0 op_sel_hi:[1,1,0]
	v_pk_fma_f32 v[244:245], v[244:245], v[36:37], 1.0 op_sel_hi:[1,1,0]
	v_pk_fma_f32 v[246:247], v[246:247], v[38:39], 1.0 op_sel_hi:[1,1,0]
	v_pk_mul_f32 v[176:177], v[176:177], v[240:241]
	v_pk_mul_f32 v[178:179], v[178:179], v[242:243]
	v_pk_mul_f32 v[180:181], v[180:181], v[244:245]
	v_pk_mul_f32 v[182:183], v[182:183], v[246:247]
	v_pk_mul_f32 v[240:241], v[168:169], v[176:177]
	v_pk_mul_f32 v[242:243], v[170:171], v[178:179]
	v_pk_mul_f32 v[244:245], v[172:173], v[180:181]
	v_pk_mul_f32 v[246:247], v[174:175], v[182:183]
	v_pk_mul_f32 v[240:241], v[240:241], v[40:41]
	v_pk_mul_f32 v[242:243], v[242:243], v[42:43]
	v_pk_mul_f32 v[244:245], v[244:245], v[44:45]
	v_pk_mul_f32 v[246:247], v[246:247], v[46:47]
	v_pk_add_f32 v[168:169], v[240:241], v[242:243]
	v_pk_add_f32 v[170:171], v[244:245], v[246:247]
	v_pk_add_f32 v[168:169], v[168:169], v[170:171]
	v_add_f32_e32 v248, v168, v169
	s_nop 1
	v_add_f32_dpp v248, v248, v248 quad_perm:[1,0,3,2] row_mask:0xf bank_mask:0xf bound_ctrl:1
	s_nop 1
	v_add_f32_dpp v248, v248, v248 quad_perm:[2,3,0,1] row_mask:0xf bank_mask:0xf bound_ctrl:1
	s_nop 1
	v_add_f32_dpp v248, v248, v248 row_half_mirror row_mask:0xf bank_mask:0xf bound_ctrl:1
	v_lshlrev_b32_e32 v232, 16, v148
	v_and_b32_e32 v233, 0xffff0000, v148
	v_lshlrev_b32_e32 v234, 16, v149
	v_and_b32_e32 v235, 0xffff0000, v149
	v_lshlrev_b32_e32 v236, 16, v150
	v_and_b32_e32 v237, 0xffff0000, v150
	v_lshlrev_b32_e32 v238, 16, v151
	v_and_b32_e32 v239, 0xffff0000, v151
	v_pk_add_f32 v[168:169], v[232:233], v[234:235]
	v_pk_add_f32 v[170:171], v[236:237], v[238:239]
	v_pk_add_f32 v[168:169], v[168:169], v[170:171]
	v_add_f32_e32 v250, v168, v169
	s_nop 1
	v_add_f32_dpp v250, v250, v250 quad_perm:[1,0,3,2] row_mask:0xf bank_mask:0xf bound_ctrl:1
	s_nop 1
	v_add_f32_dpp v250, v250, v250 quad_perm:[2,3,0,1] row_mask:0xf bank_mask:0xf bound_ctrl:1
	s_nop 1
	v_add_f32_dpp v250, v250, v250 row_half_mirror row_mask:0xf bank_mask:0xf bound_ctrl:1
	v_pk_fma_f32 v[232:233], v[250:251], v[68:69], v[232:233] op_sel_hi:[0,1,1]
	v_pk_fma_f32 v[234:235], v[250:251], v[68:69], v[234:235] op_sel_hi:[0,1,1]
	v_pk_fma_f32 v[236:237], v[250:251], v[68:69], v[236:237] op_sel_hi:[0,1,1]
	v_pk_fma_f32 v[238:239], v[250:251], v[68:69], v[238:239] op_sel_hi:[0,1,1]
	v_pk_mul_f32 v[240:241], v[232:233], v[232:233]
	v_pk_mul_f32 v[242:243], v[234:235], v[234:235]
	v_pk_mul_f32 v[244:245], v[236:237], v[236:237]
	v_pk_mul_f32 v[246:247], v[238:239], v[238:239]
	v_pk_add_f32 v[168:169], v[240:241], v[242:243]
	v_pk_add_f32 v[170:171], v[244:245], v[246:247]
	v_pk_add_f32 v[168:169], v[168:169], v[170:171]
	v_add_f32_e32 v66, v168, v169
	s_nop 1
	v_add_f32_dpp v66, v66, v66 quad_perm:[1,0,3,2] row_mask:0xf bank_mask:0xf bound_ctrl:1
	s_nop 1
	v_add_f32_dpp v66, v66, v66 quad_perm:[2,3,0,1] row_mask:0xf bank_mask:0xf bound_ctrl:1
	s_nop 1
	v_add_f32_dpp v66, v66, v66 row_half_mirror row_mask:0xf bank_mask:0xf bound_ctrl:1
	s_nop 0
	v_fmamk_f32 v66, v66, 0x3c800000, v67
	v_rsq_f32_e32 v66, v66
	s_nop 0
	v_pk_mul_f32 v[232:233], v[232:233], v[66:67] op_sel_hi:[1,0]
	v_pk_mul_f32 v[234:235], v[234:235], v[66:67] op_sel_hi:[1,0]
	v_pk_mul_f32 v[236:237], v[236:237], v[66:67] op_sel_hi:[1,0]
	v_pk_mul_f32 v[238:239], v[238:239], v[66:67] op_sel_hi:[1,0]
	v_pk_fma_f32 v[232:233], v[232:233], v[48:49], v[56:57]
	v_pk_fma_f32 v[234:235], v[234:235], v[50:51], v[58:59]
	v_pk_fma_f32 v[236:237], v[236:237], v[52:53], v[60:61]
	v_pk_fma_f32 v[238:239], v[238:239], v[54:55], v[62:63]
	v_pk_fma_f32 v[232:233], v[184:185], v[248:249], v[232:233] op_sel_hi:[1,0,1]
	v_pk_fma_f32 v[234:235], v[186:187], v[248:249], v[234:235] op_sel_hi:[1,0,1]
	v_pk_fma_f32 v[236:237], v[188:189], v[248:249], v[236:237] op_sel_hi:[1,0,1]
	v_pk_fma_f32 v[238:239], v[190:191], v[248:249], v[238:239] op_sel_hi:[1,0,1]
	v_pk_mul_f32 v[232:233], v[232:233], v[216:217]
	v_pk_mul_f32 v[234:235], v[234:235], v[218:219]
	v_pk_mul_f32 v[236:237], v[236:237], v[220:221]
	v_pk_mul_f32 v[238:239], v[238:239], v[222:223]
	v_cvt_pk_bf16_f32 v192, v232, v233
	v_cvt_pk_bf16_f32 v193, v234, v235
	v_cvt_pk_bf16_f32 v194, v236, v237
	v_cvt_pk_bf16_f32 v195, v238, v239
	s_lshr_b32 s0, s9, 1
	s_lshl_b32 s0, s0, 12
	s_add_u32 s42, s6, s0
	s_addc_u32 s43, s7, 0
	s_add_u32 s42, s42, 0x1fb00800
	s_addc_u32 s43, s43, 0
	global_store_dwordx4 v0, v[192:195], s[42:43]
	s_mov_b32 s9, s13
	s_cmp_lt_i32 s9, 0x8000
	s_cbranch_scc1 .Lpost_loop_hv
	s_branch .Lpost_done
.Lpost_nov:
	s_lshr_b32 s0, s9, 1
	s_mul_i32 s1, s0, 0x2400
	s_add_u32 s18, s14, s1
	s_addc_u32 s19, s15, 0
	s_and_b32 s1, s0, 0xfff
	s_cmp_eq_u32 s1, 0
	s_cselect_b32 s1, 0, 0x2400
	s_sub_u32 s20, s18, s1
	s_subb_u32 s21, s19, 0
	s_lshl_b32 s1, s0, 11
	s_add_u32 s22, s6, s1
	s_addc_u32 s23, s7, 0
	s_add_u32 s38, s22, 0x23b00000
	s_addc_u32 s39, s23, 0
	s_add_u32 s34, s22, 0x26700000
	s_addc_u32 s35, s23, 0
	s_add_u32 s24, s22, 0x35700000
	s_addc_u32 s25, s23, 0
	s_add_u32 s30, s22, 0x37700000
	s_addc_u32 s31, s23, 0
	s_add_u32 s22, s22, 0x33700000
	s_addc_u32 s23, s23, 0
	global_load_dwordx4 v[72:75], v0, s[18:19] offset:-2048
	global_load_dwordx4 v[76:79], v0, s[18:19]
	global_load_dwordx4 v[80:83], v0, s[18:19] offset:2048
	global_load_dwordx4 v[84:87], v0, s[20:21] offset:-2048
	global_load_dwordx4 v[88:91], v0, s[20:21]
	global_load_dwordx4 v[92:95], v0, s[20:21] offset:2048
	global_load_dwordx4 v[96:99], v0, s[22:23]
	global_load_dwordx4 v[100:103], v0, s[24:25]
	global_load_dwordx4 v[104:107], v0, s[38:39]
.Lpost_loop_nv:
	s_add_i32 s13, s9, s8
	s_cmp_lt_i32 s13, 0x8000
	s_cbranch_scc0 .Lpost_last_nv_0
	s_lshr_b32 s0, s13, 1
	s_mul_i32 s1, s0, 0x2400
	s_add_u32 s18, s14, s1
	s_addc_u32 s19, s15, 0
	s_and_b32 s1, s0, 0xfff
	s_cmp_eq_u32 s1, 0
	s_cselect_b32 s1, 0, 0x2400
	s_sub_u32 s20, s18, s1
	s_subb_u32 s21, s19, 0
	s_lshl_b32 s1, s0, 11
	s_add_u32 s22, s6, s1
	s_addc_u32 s23, s7, 0
	s_add_u32 s38, s22, 0x23b00000
	s_addc_u32 s39, s23, 0
	s_add_u32 s34, s22, 0x26700000
	s_addc_u32 s35, s23, 0
	s_add_u32 s24, s22, 0x35700000
	s_addc_u32 s25, s23, 0
	s_add_u32 s30, s22, 0x37700000
	s_addc_u32 s31, s23, 0
	s_add_u32 s22, s22, 0x33700000
	s_addc_u32 s23, s23, 0
	global_load_dwordx4 v[116:119], v0, s[18:19] offset:-2048
	global_load_dwordx4 v[120:123], v0, s[18:19]
	global_load_dwordx4 v[124:127], v0, s[18:19] offset:2048
	global_load_dwordx4 v[128:131], v0, s[20:21] offset:-2048
	global_load_dwordx4 v[132:135], v0, s[20:21]
	global_load_dwordx4 v[136:139], v0, s[20:21] offset:2048
	global_load_dwordx4 v[140:143], v0, s[22:23]
	global_load_dwordx4 v[144:147], v0, s[24:25]
	global_load_dwordx4 v[148:151], v0, s[38:39]
	s_waitcnt vmcnt(9)
	s_branch .Lpost_go_nv_0

.Lpd_nv0_184:
	v_pk_add_f32 v[232:233], v[232:233], v[184:185] neg_lo:[0,1] neg_hi:[0,1]
	v_pk_add_f32 v[234:235], v[234:235], v[186:187] neg_lo:[0,1] neg_hi:[0,1]
	v_pk_add_f32 v[236:237], v[236:237], v[188:189] neg_lo:[0,1] neg_hi:[0,1]
	v_pk_add_f32 v[238:239], v[238:239], v[190:191] neg_lo:[0,1] neg_hi:[0,1]
	v_pk_fma_f32 v[184:185], v[232:233], v[24:25], v[184:185]
	v_pk_fma_f32 v[186:187], v[234:235], v[26:27], v[186:187]
	v_pk_fma_f32 v[188:189], v[236:237], v[28:29], v[188:189]
	v_pk_fma_f32 v[190:191], v[238:239], v[30:31], v[190:191]
	v_lshlrev_b32_e32 v208, 16, v96
	v_and_b32_e32 v209, 0xffff0000, v96
	v_lshlrev_b32_e32 v210, 16, v97
	v_and_b32_e32 v211, 0xffff0000, v97
	v_lshlrev_b32_e32 v212, 16, v98
	v_and_b32_e32 v213, 0xffff0000, v98
	v_lshlrev_b32_e32 v214, 16, v99
	v_and_b32_e32 v215, 0xffff0000, v99
	v_lshlrev_b32_e32 v216, 16, v100
	v_and_b32_e32 v217, 0xffff0000, v100
	v_lshlrev_b32_e32 v218, 16, v101
	v_and_b32_e32 v219, 0xffff0000, v101
	v_lshlrev_b32_e32 v220, 16, v102
	v_and_b32_e32 v221, 0xffff0000, v102
	v_lshlrev_b32_e32 v222, 16, v103
	v_and_b32_e32 v223, 0xffff0000, v103
	v_cvt_pk_bf16_f32 v192, v184, v185
	v_cvt_pk_bf16_f32 v193, v186, v187
	v_cvt_pk_bf16_f32 v194, v188, v189
	v_cvt_pk_bf16_f32 v195, v190, v191
	s_lshr_b32 s0, s9, 1
	s_lshl_b32 s0, s0, 11
	s_add_u32 s42, s6, s0
	s_addc_u32 s43, s7, 0
	s_add_u32 s42, s42, 0x26700000
	s_addc_u32 s43, s43, 0
	global_store_dwordx4 v0, v[192:195], s[42:43]
	v_pk_add_f32 v[240:241], v[208:209], -1.0 op_sel_hi:[1,0]
	v_pk_add_f32 v[242:243], v[210:211], -1.0 op_sel_hi:[1,0]
	v_pk_add_f32 v[244:245], v[212:213], -1.0 op_sel_hi:[1,0]
	v_pk_add_f32 v[246:247], v[214:215], -1.0 op_sel_hi:[1,0]
	v_pk_fma_f32 v[240:241], v[240:241], v[32:33], 1.0 op_sel_hi:[1,1,0]
	v_pk_fma_f32 v[242:243], v[242:243], v[34:35], 1.0 op_sel_hi:[1,1,0]
	v_pk_fma_f32 v[244:245], v[244:245], v[36:37], 1.0 op_sel_hi:[1,1,0]
	v_pk_fma_f32 v[246:247], v[246:247], v[38:39], 1.0 op_sel_hi:[1,1,0]
	v_pk_mul_f32 v[176:177], v[176:177], v[240:241]
	v_pk_mul_f32 v[178:179], v[178:179], v[242:243]
	v_pk_mul_f32 v[180:181], v[180:181], v[244:245]
	v_pk_mul_f32 v[182:183], v[182:183], v[246:247]
	v_pk_mul_f32 v[240:241], v[168:169], v[176:177]
	v_pk_mul_f32 v[242:243], v[170:171], v[178:179]
	v_pk_mul_f32 v[244:245], v[172:173], v[180:181]
	v_pk_mul_f32 v[246:247], v[174:175], v[182:183]
	v_pk_mul_f32 v[240:241], v[240:241], v[40:41]
	v_pk_mul_f32 v[242:243], v[242:243], v[42:43]
	v_pk_mul_f32 v[244:245], v[244:245], v[44:45]
	v_pk_mul_f32 v[246:247], v[246:247], v[46:47]
	v_pk_add_f32 v[168:169], v[240:241], v[242:243]
	v_pk_add_f32 v[170:171], v[244:245], v[246:247]
	v_pk_add_f32 v[168:169], v[168:169], v[170:171]
	v_add_f32_e32 v248, v168, v169
	s_nop 1
	v_add_f32_dpp v248, v248, v248 quad_perm:[1,0,3,2] row_mask:0xf bank_mask:0xf bound_ctrl:1
	s_nop 1
	v_add_f32_dpp v248, v248, v248 quad_perm:[2,3,0,1] row_mask:0xf bank_mask:0xf bound_ctrl:1
	s_nop 1
	v_add_f32_dpp v248, v248, v248 row_half_mirror row_mask:0xf bank_mask:0xf bound_ctrl:1
	v_lshlrev_b32_e32 v232, 16, v104
	v_and_b32_e32 v233, 0xffff0000, v104
	v_lshlrev_b32_e32 v234, 16, v105
	v_and_b32_e32 v235, 0xffff0000, v105
	v_lshlrev_b32_e32 v236, 16, v106
	v_and_b32_e32 v237, 0xffff0000, v106
	v_lshlrev_b32_e32 v238, 16, v107
	v_and_b32_e32 v239, 0xffff0000, v107
	v_pk_add_f32 v[168:169], v[232:233], v[234:235]
	v_pk_add_f32 v[170:171], v[236:237], v[238:239]
	v_pk_add_f32 v[168:169], v[168:169], v[170:171]
	v_add_f32_e32 v250, v168, v169
	s_nop 1
	v_add_f32_dpp v250, v250, v250 quad_perm:[1,0,3,2] row_mask:0xf bank_mask:0xf bound_ctrl:1
	s_nop 1
	v_add_f32_dpp v250, v250, v250 quad_perm:[2,3,0,1] row_mask:0xf bank_mask:0xf bound_ctrl:1
	s_nop 1
	v_add_f32_dpp v250, v250, v250 row_half_mirror row_mask:0xf bank_mask:0xf bound_ctrl:1
	v_pk_fma_f32 v[232:233], v[250:251], v[68:69], v[232:233] op_sel_hi:[0,1,1]
	v_pk_fma_f32 v[234:235], v[250:251], v[68:69], v[234:235] op_sel_hi:[0,1,1]
	v_pk_fma_f32 v[236:237], v[250:251], v[68:69], v[236:237] op_sel_hi:[0,1,1]
	v_pk_fma_f32 v[238:239], v[250:251], v[68:69], v[238:239] op_sel_hi:[0,1,1]
	v_pk_mul_f32 v[240:241], v[232:233], v[232:233]
	v_pk_mul_f32 v[242:243], v[234:235], v[234:235]
	v_pk_mul_f32 v[244:245], v[236:237], v[236:237]
	v_pk_mul_f32 v[246:247], v[238:239], v[238:239]
	v_pk_add_f32 v[168:169], v[240:241], v[242:243]
	v_pk_add_f32 v[170:171], v[244:245], v[246:247]
	v_pk_add_f32 v[168:169], v[168:169], v[170:171]
	v_add_f32_e32 v66, v168, v169
	s_nop 1
	v_add_f32_dpp v66, v66, v66 quad_perm:[1,0,3,2] row_mask:0xf bank_mask:0xf bound_ctrl:1
	s_nop 1
	v_add_f32_dpp v66, v66, v66 quad_perm:[2,3,0,1] row_mask:0xf bank_mask:0xf bound_ctrl:1
	s_nop 1
	v_add_f32_dpp v66, v66, v66 row_half_mirror row_mask:0xf bank_mask:0xf bound_ctrl:1
	s_nop 0
	v_fmamk_f32 v66, v66, 0x3c800000, v67
	v_rsq_f32_e32 v66, v66
	s_nop 0
	v_pk_mul_f32 v[232:233], v[232:233], v[66:67] op_sel_hi:[1,0]
	v_pk_mul_f32 v[234:235], v[234:235], v[66:67] op_sel_hi:[1,0]
	v_pk_mul_f32 v[236:237], v[236:237], v[66:67] op_sel_hi:[1,0]
	v_pk_mul_f32 v[238:239], v[238:239], v[66:67] op_sel_hi:[1,0]
	v_pk_fma_f32 v[232:233], v[232:233], v[48:49], v[56:57]
	v_pk_fma_f32 v[234:235], v[234:235], v[50:51], v[58:59]
	v_pk_fma_f32 v[236:237], v[236:237], v[52:53], v[60:61]
	v_pk_fma_f32 v[238:239], v[238:239], v[54:55], v[62:63]
	v_pk_fma_f32 v[232:233], v[184:185], v[248:249], v[232:233] op_sel_hi:[1,0,1]
	v_pk_fma_f32 v[234:235], v[186:187], v[248:249], v[234:235] op_sel_hi:[1,0,1]
	v_pk_fma_f32 v[236:237], v[188:189], v[248:249], v[236:237] op_sel_hi:[1,0,1]
	v_pk_fma_f32 v[238:239], v[190:191], v[248:249], v[238:239] op_sel_hi:[1,0,1]
	v_pk_mul_f32 v[232:233], v[232:233], v[216:217]
	v_pk_mul_f32 v[234:235], v[234:235], v[218:219]
	v_pk_mul_f32 v[236:237], v[236:237], v[220:221]
	v_pk_mul_f32 v[238:239], v[238:239], v[222:223]
	v_cvt_pk_bf16_f32 v192, v232, v233
	v_cvt_pk_bf16_f32 v193, v234, v235
	v_cvt_pk_bf16_f32 v194, v236, v237
	v_cvt_pk_bf16_f32 v195, v238, v239
	s_lshr_b32 s0, s9, 1
	s_lshl_b32 s0, s0, 12
	s_add_u32 s42, s6, s0
	s_addc_u32 s43, s7, 0
	s_add_u32 s42, s42, 0x1fb00800
	s_addc_u32 s43, s43, 0
	global_store_dwordx4 v0, v[192:195], s[42:43]
	s_mov_b32 s9, s13
	s_cmp_lt_i32 s9, 0x8000
	s_cbranch_scc0 .Lpost_done
	s_add_i32 s13, s9, s8
	s_cmp_lt_i32 s13, 0x8000
	s_cbranch_scc0 .Lpost_last_nv_1
	s_lshr_b32 s0, s13, 1
	s_mul_i32 s1, s0, 0x2400
	s_add_u32 s18, s14, s1
	s_addc_u32 s19, s15, 0
	s_and_b32 s1, s0, 0xfff
	s_cmp_eq_u32 s1, 0
	s_cselect_b32 s1, 0, 0x2400
	s_sub_u32 s20, s18, s1
	s_subb_u32 s21, s19, 0
	s_lshl_b32 s1, s0, 11
	s_add_u32 s22, s6, s1
	s_addc_u32 s23, s7, 0
	s_add_u32 s38, s22, 0x23b00000
	s_addc_u32 s39, s23, 0
	s_add_u32 s34, s22, 0x26700000
	s_addc_u32 s35, s23, 0
	s_add_u32 s24, s22, 0x35700000
	s_addc_u32 s25, s23, 0
	s_add_u32 s30, s22, 0x37700000
	s_addc_u32 s31, s23, 0
	s_add_u32 s22, s22, 0x33700000
	s_addc_u32 s23, s23, 0
	global_load_dwordx4 v[72:75], v0, s[18:19] offset:-2048
	global_load_dwordx4 v[76:79], v0, s[18:19]
	global_load_dwordx4 v[80:83], v0, s[18:19] offset:2048
	global_load_dwordx4 v[84:87], v0, s[20:21] offset:-2048
	global_load_dwordx4 v[88:91], v0, s[20:21]
	global_load_dwordx4 v[92:95], v0, s[20:21] offset:2048
	global_load_dwordx4 v[96:99], v0, s[22:23]
	global_load_dwordx4 v[100:103], v0, s[24:25]
	global_load_dwordx4 v[104:107], v0, s[38:39]
	s_waitcnt vmcnt(9)
	s_branch .Lpost_go_nv_1

.Lpd_nv1_184:
	v_pk_add_f32 v[232:233], v[232:233], v[184:185] neg_lo:[0,1] neg_hi:[0,1]
	v_pk_add_f32 v[234:235], v[234:235], v[186:187] neg_lo:[0,1] neg_hi:[0,1]
	v_pk_add_f32 v[236:237], v[236:237], v[188:189] neg_lo:[0,1] neg_hi:[0,1]
	v_pk_add_f32 v[238:239], v[238:239], v[190:191] neg_lo:[0,1] neg_hi:[0,1]
	v_pk_fma_f32 v[184:185], v[232:233], v[24:25], v[184:185]
	v_pk_fma_f32 v[186:187], v[234:235], v[26:27], v[186:187]
	v_pk_fma_f32 v[188:189], v[236:237], v[28:29], v[188:189]
	v_pk_fma_f32 v[190:191], v[238:239], v[30:31], v[190:191]
	v_lshlrev_b32_e32 v208, 16, v140
	v_and_b32_e32 v209, 0xffff0000, v140
	v_lshlrev_b32_e32 v210, 16, v141
	v_and_b32_e32 v211, 0xffff0000, v141
	v_lshlrev_b32_e32 v212, 16, v142
	v_and_b32_e32 v213, 0xffff0000, v142
	v_lshlrev_b32_e32 v214, 16, v143
	v_and_b32_e32 v215, 0xffff0000, v143
	v_lshlrev_b32_e32 v216, 16, v144
	v_and_b32_e32 v217, 0xffff0000, v144
	v_lshlrev_b32_e32 v218, 16, v145
	v_and_b32_e32 v219, 0xffff0000, v145
	v_lshlrev_b32_e32 v220, 16, v146
	v_and_b32_e32 v221, 0xffff0000, v146
	v_lshlrev_b32_e32 v222, 16, v147
	v_and_b32_e32 v223, 0xffff0000, v147
	v_cvt_pk_bf16_f32 v192, v184, v185
	v_cvt_pk_bf16_f32 v193, v186, v187
	v_cvt_pk_bf16_f32 v194, v188, v189
	v_cvt_pk_bf16_f32 v195, v190, v191
	s_lshr_b32 s0, s9, 1
	s_lshl_b32 s0, s0, 11
	s_add_u32 s42, s6, s0
	s_addc_u32 s43, s7, 0
	s_add_u32 s42, s42, 0x26700000
	s_addc_u32 s43, s43, 0
	global_store_dwordx4 v0, v[192:195], s[42:43]
	v_pk_add_f32 v[240:241], v[208:209], -1.0 op_sel_hi:[1,0]
	v_pk_add_f32 v[242:243], v[210:211], -1.0 op_sel_hi:[1,0]
	v_pk_add_f32 v[244:245], v[212:213], -1.0 op_sel_hi:[1,0]
	v_pk_add_f32 v[246:247], v[214:215], -1.0 op_sel_hi:[1,0]
	v_pk_fma_f32 v[240:241], v[240:241], v[32:33], 1.0 op_sel_hi:[1,1,0]
	v_pk_fma_f32 v[242:243], v[242:243], v[34:35], 1.0 op_sel_hi:[1,1,0]
	v_pk_fma_f32 v[244:245], v[244:245], v[36:37], 1.0 op_sel_hi:[1,1,0]
	v_pk_fma_f32 v[246:247], v[246:247], v[38:39], 1.0 op_sel_hi:[1,1,0]
	v_pk_mul_f32 v[176:177], v[176:177], v[240:241]
	v_pk_mul_f32 v[178:179], v[178:179], v[242:243]
	v_pk_mul_f32 v[180:181], v[180:181], v[244:245]
	v_pk_mul_f32 v[182:183], v[182:183], v[246:247]
	v_pk_mul_f32 v[240:241], v[168:169], v[176:177]
	v_pk_mul_f32 v[242:243], v[170:171], v[178:179]
	v_pk_mul_f32 v[244:245], v[172:173], v[180:181]
	v_pk_mul_f32 v[246:247], v[174:175], v[182:183]
	v_pk_mul_f32 v[240:241], v[240:241], v[40:41]
	v_pk_mul_f32 v[242:243], v[242:243], v[42:43]
	v_pk_mul_f32 v[244:245], v[244:245], v[44:45]
	v_pk_mul_f32 v[246:247], v[246:247], v[46:47]
	v_pk_add_f32 v[168:169], v[240:241], v[242:243]
	v_pk_add_f32 v[170:171], v[244:245], v[246:247]
	v_pk_add_f32 v[168:169], v[168:169], v[170:171]
	v_add_f32_e32 v248, v168, v169
	s_nop 1
	v_add_f32_dpp v248, v248, v248 quad_perm:[1,0,3,2] row_mask:0xf bank_mask:0xf bound_ctrl:1
	s_nop 1
	v_add_f32_dpp v248, v248, v248 quad_perm:[2,3,0,1] row_mask:0xf bank_mask:0xf bound_ctrl:1
	s_nop 1
	v_add_f32_dpp v248, v248, v248 row_half_mirror row_mask:0xf bank_mask:0xf bound_ctrl:1
	v_lshlrev_b32_e32 v232, 16, v148
	v_and_b32_e32 v233, 0xffff0000, v148
	v_lshlrev_b32_e32 v234, 16, v149
	v_and_b32_e32 v235, 0xffff0000, v149
	v_lshlrev_b32_e32 v236, 16, v150
	v_and_b32_e32 v237, 0xffff0000, v150
	v_lshlrev_b32_e32 v238, 16, v151
	v_and_b32_e32 v239, 0xffff0000, v151
	v_pk_add_f32 v[168:169], v[232:233], v[234:235]
	v_pk_add_f32 v[170:171], v[236:237], v[238:239]
	v_pk_add_f32 v[168:169], v[168:169], v[170:171]
	v_add_f32_e32 v250, v168, v169
	s_nop 1
	v_add_f32_dpp v250, v250, v250 quad_perm:[1,0,3,2] row_mask:0xf bank_mask:0xf bound_ctrl:1
	s_nop 1
	v_add_f32_dpp v250, v250, v250 quad_perm:[2,3,0,1] row_mask:0xf bank_mask:0xf bound_ctrl:1
	s_nop 1
	v_add_f32_dpp v250, v250, v250 row_half_mirror row_mask:0xf bank_mask:0xf bound_ctrl:1
	v_pk_fma_f32 v[232:233], v[250:251], v[68:69], v[232:233] op_sel_hi:[0,1,1]
	v_pk_fma_f32 v[234:235], v[250:251], v[68:69], v[234:235] op_sel_hi:[0,1,1]
	v_pk_fma_f32 v[236:237], v[250:251], v[68:69], v[236:237] op_sel_hi:[0,1,1]
	v_pk_fma_f32 v[238:239], v[250:251], v[68:69], v[238:239] op_sel_hi:[0,1,1]
	v_pk_mul_f32 v[240:241], v[232:233], v[232:233]
	v_pk_mul_f32 v[242:243], v[234:235], v[234:235]
	v_pk_mul_f32 v[244:245], v[236:237], v[236:237]
	v_pk_mul_f32 v[246:247], v[238:239], v[238:239]
	v_pk_add_f32 v[168:169], v[240:241], v[242:243]
	v_pk_add_f32 v[170:171], v[244:245], v[246:247]
	v_pk_add_f32 v[168:169], v[168:169], v[170:171]
	v_add_f32_e32 v66, v168, v169
	s_nop 1
	v_add_f32_dpp v66, v66, v66 quad_perm:[1,0,3,2] row_mask:0xf bank_mask:0xf bound_ctrl:1
	s_nop 1
	v_add_f32_dpp v66, v66, v66 quad_perm:[2,3,0,1] row_mask:0xf bank_mask:0xf bound_ctrl:1
	s_nop 1
	v_add_f32_dpp v66, v66, v66 row_half_mirror row_mask:0xf bank_mask:0xf bound_ctrl:1
	s_nop 0
	v_fmamk_f32 v66, v66, 0x3c800000, v67
	v_rsq_f32_e32 v66, v66
	s_nop 0
	v_pk_mul_f32 v[232:233], v[232:233], v[66:67] op_sel_hi:[1,0]
	v_pk_mul_f32 v[234:235], v[234:235], v[66:67] op_sel_hi:[1,0]
	v_pk_mul_f32 v[236:237], v[236:237], v[66:67] op_sel_hi:[1,0]
	v_pk_mul_f32 v[238:239], v[238:239], v[66:67] op_sel_hi:[1,0]
	v_pk_fma_f32 v[232:233], v[232:233], v[48:49], v[56:57]
	v_pk_fma_f32 v[234:235], v[234:235], v[50:51], v[58:59]
	v_pk_fma_f32 v[236:237], v[236:237], v[52:53], v[60:61]
	v_pk_fma_f32 v[238:239], v[238:239], v[54:55], v[62:63]
	v_pk_fma_f32 v[232:233], v[184:185], v[248:249], v[232:233] op_sel_hi:[1,0,1]
	v_pk_fma_f32 v[234:235], v[186:187], v[248:249], v[234:235] op_sel_hi:[1,0,1]
	v_pk_fma_f32 v[236:237], v[188:189], v[248:249], v[236:237] op_sel_hi:[1,0,1]
	v_pk_fma_f32 v[238:239], v[190:191], v[248:249], v[238:239] op_sel_hi:[1,0,1]
	v_pk_mul_f32 v[232:233], v[232:233], v[216:217]
	v_pk_mul_f32 v[234:235], v[234:235], v[218:219]
	v_pk_mul_f32 v[236:237], v[236:237], v[220:221]
	v_pk_mul_f32 v[238:239], v[238:239], v[222:223]
	v_cvt_pk_bf16_f32 v192, v232, v233
	v_cvt_pk_bf16_f32 v193, v234, v235
	v_cvt_pk_bf16_f32 v194, v236, v237
	v_cvt_pk_bf16_f32 v195, v238, v239
	s_lshr_b32 s0, s9, 1
	s_lshl_b32 s0, s0, 12
	s_add_u32 s42, s6, s0
	s_addc_u32 s43, s7, 0
	s_add_u32 s42, s42, 0x1fb00800
	s_addc_u32 s43, s43, 0
	global_store_dwordx4 v0, v[192:195], s[42:43]
	s_mov_b32 s9, s13
	s_cmp_lt_i32 s9, 0x8000
	s_cbranch_scc1 .Lpost_loop_nv
.Lpost_done:
.LBB0_181:
	s_or_b64 exec, exec, s[4:5]
	s_mov_b64 s[4:5], 0
